# P13 weight-transpose items (W13 with gamma fold, W2, Wout etc.): all 16 row loads + 16 scale loads of an item issued together with counted vmcnt, instead of 16 serial round trips
# speedup vs baseline: 1.0136x; 1.0105x over previous
; #define LAS __attribute__((address_space(3)))
; __device__ __forceinline__ unsigned pk2(float lo, float hi) { return pg8::cvt_pk_bf16(lo, hi); }
; __device__ __forceinline__ void transpose_item(const float* W, int ldw, int K, const float* gain, bf16* WT, int kb, int scol0, int drow0, LAS float* scr, int lane) {
;     const int k0 = 64 * kb;
; #pragma unroll 4
;     for (int i = 0; i < 16; ++i) { const int kk = 4 * i + (lane >> 4); f32x4 w = *(const f32x4*)(W + (size_t)(k0 + kk) * ldw + scol0 + 4 * (lane & 15)); if (gain) w = w * gain[k0 + kk];
;         LAS float* d = scr + kk * 65 + 4 * (lane & 15); d[0] = w[0]; d[1] = w[1]; d[2] = w[2]; d[3] = w[3]; }
;     asm volatile("s_waitcnt lgkmcnt(0)" ::: "memory");
;     const int c = lane & 7;
; #pragma unroll
;     for (int j = 0; j < 8; ++j) { const int n = (lane >> 3) + 8 * j; const LAS float* p = scr + (8 * c) * 65 + n;
;         v4u o; o.x = pk2(p[0 * 65], p[1 * 65]); o.y = pk2(p[2 * 65], p[3 * 65]); o.z = pk2(p[4 * 65], p[5 * 65]); o.w = pk2(p[6 * 65], p[7 * 65]);
;         *(v4u*)(WT + (size_t)(drow0 + n) * K + k0 + 8 * c) = o; }
.LBB0_146:
	v_lshl_add_u64 v[20:21], v[18:19], 0, s[16:17]
	global_load_dwordx4 v[60:63], v[20:21], off
	v_lshl_add_u64 v[20:21], v[16:17], 0, s[16:17]
	global_load_dwordx4 v[64:67], v[20:21], off
	v_lshl_add_u64 v[20:21], v[2:3], 0, s[16:17]
	global_load_dwordx4 v[68:71], v[20:21], off
	v_lshl_add_u64 v[20:21], v[0:1], 0, s[16:17]
	global_load_dwordx4 v[72:75], v[20:21], off
	s_add_u32 s16, s16, 0x10000
	s_addc_u32 s17, s17, 0
	v_lshl_add_u64 v[20:21], v[18:19], 0, s[16:17]
	global_load_dwordx4 v[76:79], v[20:21], off
	v_lshl_add_u64 v[20:21], v[16:17], 0, s[16:17]
	global_load_dwordx4 v[80:83], v[20:21], off
	v_lshl_add_u64 v[20:21], v[2:3], 0, s[16:17]
	global_load_dwordx4 v[84:87], v[20:21], off
	v_lshl_add_u64 v[20:21], v[0:1], 0, s[16:17]
	global_load_dwordx4 v[88:91], v[20:21], off
	s_add_u32 s16, s16, 0x10000
	s_addc_u32 s17, s17, 0
	v_lshl_add_u64 v[20:21], v[18:19], 0, s[16:17]
	global_load_dwordx4 v[92:95], v[20:21], off
	v_lshl_add_u64 v[20:21], v[16:17], 0, s[16:17]
	global_load_dwordx4 v[96:99], v[20:21], off
	v_lshl_add_u64 v[20:21], v[2:3], 0, s[16:17]
	global_load_dwordx4 v[100:103], v[20:21], off
	v_lshl_add_u64 v[20:21], v[0:1], 0, s[16:17]
	global_load_dwordx4 v[104:107], v[20:21], off
	s_add_u32 s16, s16, 0x10000
	s_addc_u32 s17, s17, 0
	v_lshl_add_u64 v[20:21], v[18:19], 0, s[16:17]
	global_load_dwordx4 v[108:111], v[20:21], off
	v_lshl_add_u64 v[20:21], v[16:17], 0, s[16:17]
	global_load_dwordx4 v[112:115], v[20:21], off
	v_lshl_add_u64 v[20:21], v[2:3], 0, s[16:17]
	global_load_dwordx4 v[116:119], v[20:21], off
	v_lshl_add_u64 v[20:21], v[0:1], 0, s[16:17]
	global_load_dwordx4 v[120:123], v[20:21], off
	s_add_u32 s16, s16, 0x10000
	s_addc_u32 s17, s17, 0
	s_waitcnt vmcnt(12)
	v_add_u32_e32 v15, 0x410, v6
	v_add_u32_e32 v26, 0x418, v6
	ds_write2_b32 v6, v60, v61 offset1:1
	ds_write2_b32 v6, v62, v63 offset0:2 offset1:3
	ds_write2_b32 v15, v64, v65 offset1:1
	ds_write2_b32 v26, v66, v67 offset1:1
	v_add_u32_e32 v15, 0x820, v6
	v_add_u32_e32 v26, 0x828, v6
	ds_write2_b32 v15, v68, v69 offset1:1
	ds_write2_b32 v26, v70, v71 offset1:1
	v_add_u32_e32 v15, 0xc30, v6
	v_add_u32_e32 v24, 0xc38, v6
	v_add_u32_e32 v6, 0x1040, v6
	ds_write2_b32 v15, v72, v73 offset1:1
	ds_write2_b32 v24, v74, v75 offset1:1
	s_waitcnt vmcnt(8)
	v_add_u32_e32 v15, 0x410, v6
	v_add_u32_e32 v26, 0x418, v6
	ds_write2_b32 v6, v76, v77 offset1:1
	ds_write2_b32 v6, v78, v79 offset0:2 offset1:3
	ds_write2_b32 v15, v80, v81 offset1:1
	ds_write2_b32 v26, v82, v83 offset1:1
	v_add_u32_e32 v15, 0x820, v6
	v_add_u32_e32 v26, 0x828, v6
	ds_write2_b32 v15, v84, v85 offset1:1
	ds_write2_b32 v26, v86, v87 offset1:1
	v_add_u32_e32 v15, 0xc30, v6
	v_add_u32_e32 v24, 0xc38, v6
	v_add_u32_e32 v6, 0x1040, v6
	ds_write2_b32 v15, v88, v89 offset1:1
	ds_write2_b32 v24, v90, v91 offset1:1
	s_waitcnt vmcnt(4)
	v_add_u32_e32 v15, 0x410, v6
	v_add_u32_e32 v26, 0x418, v6
	ds_write2_b32 v6, v92, v93 offset1:1
	ds_write2_b32 v6, v94, v95 offset0:2 offset1:3
	ds_write2_b32 v15, v96, v97 offset1:1
	ds_write2_b32 v26, v98, v99 offset1:1
	v_add_u32_e32 v15, 0x820, v6
	v_add_u32_e32 v26, 0x828, v6
	ds_write2_b32 v15, v100, v101 offset1:1
	ds_write2_b32 v26, v102, v103 offset1:1
	v_add_u32_e32 v15, 0xc30, v6
	v_add_u32_e32 v24, 0xc38, v6
	v_add_u32_e32 v6, 0x1040, v6
	ds_write2_b32 v15, v104, v105 offset1:1
	ds_write2_b32 v24, v106, v107 offset1:1
	s_waitcnt vmcnt(0)
	v_add_u32_e32 v15, 0x410, v6
	v_add_u32_e32 v26, 0x418, v6
	ds_write2_b32 v6, v108, v109 offset1:1
	ds_write2_b32 v6, v110, v111 offset0:2 offset1:3
	ds_write2_b32 v15, v112, v113 offset1:1
	ds_write2_b32 v26, v114, v115 offset1:1
	v_add_u32_e32 v15, 0x820, v6
	v_add_u32_e32 v26, 0x828, v6
	ds_write2_b32 v15, v116, v117 offset1:1
	ds_write2_b32 v26, v118, v119 offset1:1
	v_add_u32_e32 v15, 0xc30, v6
	v_add_u32_e32 v24, 0xc38, v6
	v_add_u32_e32 v6, 0x1040, v6
	ds_write2_b32 v15, v120, v121 offset1:1
	ds_write2_b32 v24, v122, v123 offset1:1
	s_waitcnt lgkmcnt(0)
	s_lshl_b32 s2, s31, 6
	s_lshl_b32 s17, s31, 2
	s_and_b32 s16, s2, 0x3c0
	s_and_b32 s2, s17, 0x7fffffc0
	s_addk_i32 s2, 0xd200
	s_waitcnt lgkmcnt(0)
	s_lshl_b64 s[18:19], s[2:3], 1
	ds_read2_b32 v[0:1], v29 offset1:65
	s_add_u32 s4, s4, s18
	s_waitcnt lgkmcnt(0)
	v_cvt_pk_bf16_f32 v0, v0, v1
	ds_read2_b32 v[2:3], v29 offset0:130 offset1:195
	v_lshlrev_b32_e32 v6, 1, v8
	v_add_u32_e32 v15, 0x400, v29
	v_or_b32_e32 v20, s16, v28
	s_addc_u32 s5, s5, s19
	s_waitcnt lgkmcnt(0)
; #define LAS __attribute__((address_space(3)))
; __device__ __forceinline__ unsigned pk2(float lo, float hi) { return pg8::cvt_pk_bf16(lo, hi); }
; __device__ __forceinline__ void transpose_item(const float* W, int ldw, int K, const float* gain, bf16* WT, int kb, int scol0, int drow0, LAS float* scr, int lane) {
;     ...
;     const int c = lane & 7;
; #pragma unroll
;     for (int j = 0; j < 8; ++j) { const int n = (lane >> 3) + 8 * j; const LAS float* p = scr + (8 * c) * 65 + n;
;         v4u o; o.x = pk2(p[0 * 65], p[1 * 65]); o.y = pk2(p[2 * 65], p[3 * 65]); o.z = pk2(p[4 * 65], p[5 * 65]); o.w = pk2(p[6 * 65], p[7 * 65]);
;         *(v4u*)(WT + (size_t)(drow0 + n) * K + k0 + 8 * c) = o; }
;     asm volatile("s_waitcnt lgkmcnt(0)" ::: "memory");
	v_cvt_pk_bf16_f32 v1, v2, v3
	ds_read2_b32 v[2:3], v15 offset0:4 offset1:69
	v_lshl_add_u64 v[18:19], s[4:5], 0, v[6:7]
	v_mul_u32_u24_e32 v6, 0xb00, v20
	s_waitcnt lgkmcnt(0)
	v_cvt_pk_bf16_f32 v2, v2, v3
	ds_read2_b32 v[16:17], v15 offset0:134 offset1:199
	v_lshl_add_u64 v[18:19], v[18:19], 0, s[6:7]
	v_lshlrev_b32_e32 v6, 1, v6
	s_waitcnt lgkmcnt(0)
	v_cvt_pk_bf16_f32 v3, v16, v17
	v_lshl_add_u64 v[16:17], v[18:19], 0, v[6:7]
	flat_store_dwordx4 v[16:17], v[0:3]
	ds_read2_b32 v[0:1], v29 offset0:8 offset1:73
	s_mov_b64 s[4:5], 0
	s_waitcnt lgkmcnt(0)
	v_cvt_pk_bf16_f32 v0, v0, v1
	ds_read2_b32 v[2:3], v29 offset0:138 offset1:203
	s_waitcnt lgkmcnt(0)
	v_cvt_pk_bf16_f32 v1, v2, v3
	ds_read2_b32 v[2:3], v15 offset0:12 offset1:77
	s_waitcnt lgkmcnt(0)
	v_cvt_pk_bf16_f32 v2, v2, v3
	v_or_b32_e32 v3, s16, v30
	v_mul_u32_u24_e32 v3, 0xb00, v3
	v_lshlrev_b32_e32 v6, 1, v3
	v_lshl_add_u64 v[20:21], v[18:19], 0, v[6:7]
	ds_read2_b32 v[16:17], v15 offset0:142 offset1:207
	s_waitcnt lgkmcnt(0)
	v_cvt_pk_bf16_f32 v3, v16, v17
	flat_store_dwordx4 v[20:21], v[0:3]
	ds_read2_b32 v[0:1], v29 offset0:16 offset1:81
	s_waitcnt lgkmcnt(0)
	v_cvt_pk_bf16_f32 v0, v0, v1
	ds_read2_b32 v[2:3], v29 offset0:146 offset1:211
	s_waitcnt lgkmcnt(0)
	v_cvt_pk_bf16_f32 v1, v2, v3
	ds_read2_b32 v[2:3], v15 offset0:20 offset1:85
	s_waitcnt lgkmcnt(0)
	v_cvt_pk_bf16_f32 v2, v2, v3
	v_or_b32_e32 v3, s16, v31
	v_mul_u32_u24_e32 v3, 0xb00, v3
	v_lshlrev_b32_e32 v6, 1, v3
	v_lshl_add_u64 v[20:21], v[18:19], 0, v[6:7]
	ds_read2_b32 v[16:17], v15 offset0:150 offset1:215
	s_waitcnt lgkmcnt(0)
	v_cvt_pk_bf16_f32 v3, v16, v17
	flat_store_dwordx4 v[20:21], v[0:3]
	ds_read2_b32 v[0:1], v29 offset0:24 offset1:89
	s_waitcnt lgkmcnt(0)
	v_cvt_pk_bf16_f32 v0, v0, v1
	ds_read2_b32 v[2:3], v29 offset0:154 offset1:219
	s_waitcnt lgkmcnt(0)
	v_cvt_pk_bf16_f32 v1, v2, v3
	ds_read2_b32 v[2:3], v15 offset0:28 offset1:93
	s_waitcnt lgkmcnt(0)
	v_cvt_pk_bf16_f32 v2, v2, v3
	v_or_b32_e32 v3, s16, v32
	v_mul_u32_u24_e32 v3, 0xb00, v3
	v_lshlrev_b32_e32 v6, 1, v3
	v_lshl_add_u64 v[20:21], v[18:19], 0, v[6:7]
	ds_read2_b32 v[16:17], v15 offset0:158 offset1:223
	s_waitcnt lgkmcnt(0)
	v_cvt_pk_bf16_f32 v3, v16, v17
	flat_store_dwordx4 v[20:21], v[0:3]
	ds_read2_b32 v[0:1], v29 offset0:32 offset1:97
	s_waitcnt lgkmcnt(0)
	v_cvt_pk_bf16_f32 v0, v0, v1
	ds_read2_b32 v[2:3], v29 offset0:162 offset1:227
	s_waitcnt lgkmcnt(0)
	v_cvt_pk_bf16_f32 v1, v2, v3
	ds_read2_b32 v[2:3], v15 offset0:36 offset1:101
	s_waitcnt lgkmcnt(0)
	v_cvt_pk_bf16_f32 v2, v2, v3
	v_or_b32_e32 v3, s16, v33
	v_mul_u32_u24_e32 v3, 0xb00, v3
	v_lshlrev_b32_e32 v6, 1, v3
	v_lshl_add_u64 v[20:21], v[18:19], 0, v[6:7]
	ds_read2_b32 v[16:17], v15 offset0:166 offset1:231
	s_waitcnt lgkmcnt(0)
	v_cvt_pk_bf16_f32 v3, v16, v17
	flat_store_dwordx4 v[20:21], v[0:3]
	ds_read2_b32 v[0:1], v29 offset0:40 offset1:105
	s_waitcnt lgkmcnt(0)
	v_cvt_pk_bf16_f32 v0, v0, v1
	ds_read2_b32 v[2:3], v29 offset0:170 offset1:235
	s_waitcnt lgkmcnt(0)
	v_cvt_pk_bf16_f32 v1, v2, v3
	ds_read2_b32 v[2:3], v15 offset0:44 offset1:109
	s_waitcnt lgkmcnt(0)
	v_cvt_pk_bf16_f32 v2, v2, v3
	v_or_b32_e32 v3, s16, v34
	v_mul_u32_u24_e32 v3, 0xb00, v3
	v_lshlrev_b32_e32 v6, 1, v3
	v_lshl_add_u64 v[20:21], v[18:19], 0, v[6:7]
	ds_read2_b32 v[16:17], v15 offset0:174 offset1:239
	s_waitcnt lgkmcnt(0)
	v_cvt_pk_bf16_f32 v3, v16, v17
	flat_store_dwordx4 v[20:21], v[0:3]
	ds_read2_b32 v[0:1], v29 offset0:48 offset1:113
	s_waitcnt lgkmcnt(0)
	v_cvt_pk_bf16_f32 v0, v0, v1
	ds_read2_b32 v[2:3], v29 offset0:178 offset1:243
	s_waitcnt lgkmcnt(0)
	v_cvt_pk_bf16_f32 v1, v2, v3
	ds_read2_b32 v[2:3], v15 offset0:52 offset1:117
	s_waitcnt lgkmcnt(0)
	v_cvt_pk_bf16_f32 v2, v2, v3
	v_or_b32_e32 v3, s16, v35
	v_mul_u32_u24_e32 v3, 0xb00, v3
	v_lshlrev_b32_e32 v6, 1, v3
	v_lshl_add_u64 v[20:21], v[18:19], 0, v[6:7]
	ds_read2_b32 v[16:17], v15 offset0:182 offset1:247
	s_waitcnt lgkmcnt(0)
	v_cvt_pk_bf16_f32 v3, v16, v17
	flat_store_dwordx4 v[20:21], v[0:3]
	ds_read2_b32 v[0:1], v29 offset0:56 offset1:121
	s_waitcnt lgkmcnt(0)
	v_cvt_pk_bf16_f32 v0, v0, v1
	ds_read2_b32 v[2:3], v29 offset0:186 offset1:251
	s_waitcnt lgkmcnt(0)
	v_cvt_pk_bf16_f32 v1, v2, v3
	ds_read2_b32 v[2:3], v15 offset0:60 offset1:125
	s_waitcnt lgkmcnt(0)
	v_cvt_pk_bf16_f32 v2, v2, v3
	v_or_b32_e32 v3, s16, v36
	v_mul_u32_u24_e32 v3, 0xb00, v3
	ds_read2_b32 v[16:17], v15 offset0:190 offset1:255
	v_lshlrev_b32_e32 v6, 1, v3
	s_waitcnt lgkmcnt(0)
	v_cvt_pk_bf16_f32 v3, v16, v17
	v_lshl_add_u64 v[16:17], v[18:19], 0, v[6:7]
	flat_store_dwordx4 v[16:17], v[0:3]
	s_waitcnt lgkmcnt(0)

; #define LAS __attribute__((address_space(3)))
; __device__ __forceinline__ void transpose_item(const float* W, int ldw, int K, const float* gain, bf16* WT, int kb, int scol0, int drow0, LAS float* scr, int lane) {
;     const int k0 = 64 * kb;
; #pragma unroll 4
;     for (int i = 0; i < 16; ++i) { const int kk = 4 * i + (lane >> 4); f32x4 w = *(const f32x4*)(W + (size_t)(k0 + kk) * ldw + scol0 + 4 * (lane & 15)); if (gain) w = w * gain[k0 + kk];
;         LAS float* d = scr + kk * 65 + 4 * (lane & 15); d[0] = w[0]; d[1] = w[1]; d[2] = w[2]; d[3] = w[3]; }
;     asm volatile("s_waitcnt lgkmcnt(0)" ::: "memory");
.LBB0_151:
	v_lshl_add_u64 v[0:1], v[24:25], 0, s[20:21]
	global_load_dwordx4 v[60:63], v[0:1], off
	v_lshl_add_u64 v[0:1], v[22:23], 0, s[20:21]
	global_load_dwordx4 v[64:67], v[0:1], off
	v_lshl_add_u64 v[0:1], v[20:21], 0, s[20:21]
	global_load_dwordx4 v[68:71], v[0:1], off
	v_lshl_add_u64 v[0:1], v[16:17], 0, s[20:21]
	global_load_dwordx4 v[72:75], v[0:1], off
	s_add_u32 s20, s20, 0x58000
	s_addc_u32 s21, s21, 0
	v_lshl_add_u64 v[0:1], v[24:25], 0, s[20:21]
	global_load_dwordx4 v[76:79], v[0:1], off
	v_lshl_add_u64 v[0:1], v[22:23], 0, s[20:21]
	global_load_dwordx4 v[80:83], v[0:1], off
	v_lshl_add_u64 v[0:1], v[20:21], 0, s[20:21]
	global_load_dwordx4 v[84:87], v[0:1], off
	v_lshl_add_u64 v[0:1], v[16:17], 0, s[20:21]
	global_load_dwordx4 v[88:91], v[0:1], off
	s_add_u32 s20, s20, 0x58000
	s_addc_u32 s21, s21, 0
	v_lshl_add_u64 v[0:1], v[24:25], 0, s[20:21]
	global_load_dwordx4 v[92:95], v[0:1], off
	v_lshl_add_u64 v[0:1], v[22:23], 0, s[20:21]
	global_load_dwordx4 v[96:99], v[0:1], off
	v_lshl_add_u64 v[0:1], v[20:21], 0, s[20:21]
	global_load_dwordx4 v[100:103], v[0:1], off
	v_lshl_add_u64 v[0:1], v[16:17], 0, s[20:21]
	global_load_dwordx4 v[104:107], v[0:1], off
	s_add_u32 s20, s20, 0x58000
	s_addc_u32 s21, s21, 0
	v_lshl_add_u64 v[0:1], v[24:25], 0, s[20:21]
	global_load_dwordx4 v[108:111], v[0:1], off
	v_lshl_add_u64 v[0:1], v[22:23], 0, s[20:21]
	global_load_dwordx4 v[112:115], v[0:1], off
	v_lshl_add_u64 v[0:1], v[20:21], 0, s[20:21]
	global_load_dwordx4 v[116:119], v[0:1], off
	v_lshl_add_u64 v[0:1], v[16:17], 0, s[20:21]
	global_load_dwordx4 v[120:123], v[0:1], off
	s_add_u32 s20, s20, 0x58000
	s_addc_u32 s21, s21, 0
	s_andn2_b64 vcc, exec, s[22:23]
	s_cbranch_vccnz .Lp13_nsc
	v_lshl_add_u64 v[26:27], s[18:19], 0, v[6:7]
	v_lshl_add_u64 v[0:1], s[18:19], 0, v[18:19]
	global_load_dword v160, v[26:27], off
	global_load_dword v162, v[0:1], off offset:16
	global_load_dword v164, v[0:1], off offset:32
	global_load_dword v166, v[0:1], off offset:48
	global_load_dword v168, v[26:27], off offset:64
	global_load_dword v170, v[0:1], off offset:80
	global_load_dword v172, v[0:1], off offset:96
	global_load_dword v174, v[0:1], off offset:112
	global_load_dword v176, v[26:27], off offset:128
	global_load_dword v178, v[0:1], off offset:144
	global_load_dword v180, v[0:1], off offset:160
	global_load_dword v182, v[0:1], off offset:176
	global_load_dword v184, v[26:27], off offset:192
	global_load_dword v186, v[0:1], off offset:208
	global_load_dword v188, v[0:1], off offset:224
	global_load_dword v190, v[0:1], off offset:240
	s_waitcnt vmcnt(0)
	v_pk_mul_f32 v[62:63], v[62:63], v[160:161] op_sel_hi:[1,0]
	v_pk_mul_f32 v[60:61], v[60:61], v[160:161] op_sel_hi:[1,0]
	v_pk_mul_f32 v[66:67], v[66:67], v[162:163] op_sel_hi:[1,0]
	v_pk_mul_f32 v[64:65], v[64:65], v[162:163] op_sel_hi:[1,0]
	v_pk_mul_f32 v[70:71], v[70:71], v[164:165] op_sel_hi:[1,0]
	v_pk_mul_f32 v[68:69], v[68:69], v[164:165] op_sel_hi:[1,0]
	v_pk_mul_f32 v[74:75], v[74:75], v[166:167] op_sel_hi:[1,0]
	v_pk_mul_f32 v[72:73], v[72:73], v[166:167] op_sel_hi:[1,0]
	v_pk_mul_f32 v[78:79], v[78:79], v[168:169] op_sel_hi:[1,0]
	v_pk_mul_f32 v[76:77], v[76:77], v[168:169] op_sel_hi:[1,0]
	v_pk_mul_f32 v[82:83], v[82:83], v[170:171] op_sel_hi:[1,0]
	v_pk_mul_f32 v[80:81], v[80:81], v[170:171] op_sel_hi:[1,0]
	v_pk_mul_f32 v[86:87], v[86:87], v[172:173] op_sel_hi:[1,0]
	v_pk_mul_f32 v[84:85], v[84:85], v[172:173] op_sel_hi:[1,0]
	v_pk_mul_f32 v[90:91], v[90:91], v[174:175] op_sel_hi:[1,0]
	v_pk_mul_f32 v[88:89], v[88:89], v[174:175] op_sel_hi:[1,0]
	v_pk_mul_f32 v[94:95], v[94:95], v[176:177] op_sel_hi:[1,0]
	v_pk_mul_f32 v[92:93], v[92:93], v[176:177] op_sel_hi:[1,0]
	v_pk_mul_f32 v[98:99], v[98:99], v[178:179] op_sel_hi:[1,0]
	v_pk_mul_f32 v[96:97], v[96:97], v[178:179] op_sel_hi:[1,0]
	v_pk_mul_f32 v[102:103], v[102:103], v[180:181] op_sel_hi:[1,0]
	v_pk_mul_f32 v[100:101], v[100:101], v[180:181] op_sel_hi:[1,0]
	v_pk_mul_f32 v[106:107], v[106:107], v[182:183] op_sel_hi:[1,0]
	v_pk_mul_f32 v[104:105], v[104:105], v[182:183] op_sel_hi:[1,0]
	v_pk_mul_f32 v[110:111], v[110:111], v[184:185] op_sel_hi:[1,0]
	v_pk_mul_f32 v[108:109], v[108:109], v[184:185] op_sel_hi:[1,0]
	v_pk_mul_f32 v[114:115], v[114:115], v[186:187] op_sel_hi:[1,0]
	v_pk_mul_f32 v[112:113], v[112:113], v[186:187] op_sel_hi:[1,0]
	v_pk_mul_f32 v[118:119], v[118:119], v[188:189] op_sel_hi:[1,0]
	v_pk_mul_f32 v[116:117], v[116:117], v[188:189] op_sel_hi:[1,0]
	v_pk_mul_f32 v[122:123], v[122:123], v[190:191] op_sel_hi:[1,0]
	v_pk_mul_f32 v[120:121], v[120:121], v[190:191] op_sel_hi:[1,0]
.Lp13_nsc:
	s_waitcnt vmcnt(12)
	v_add_u32_e32 v49, 0x410, v15
	v_add_u32_e32 v0, 0x418, v15
	ds_write2_b32 v15, v60, v61 offset1:1
	ds_write2_b32 v15, v62, v63 offset0:2 offset1:3
	ds_write2_b32 v49, v64, v65 offset1:1
	ds_write2_b32 v0, v66, v67 offset1:1
	v_add_u32_e32 v49, 0x820, v15
	v_add_u32_e32 v0, 0x828, v15
	ds_write2_b32 v49, v68, v69 offset1:1
	ds_write2_b32 v0, v70, v71 offset1:1
	v_add_u32_e32 v49, 0xc30, v15
	v_add_u32_e32 v0, 0xc38, v15
	v_add_u32_e32 v15, 0x1040, v15
	ds_write2_b32 v49, v72, v73 offset1:1
	ds_write2_b32 v0, v74, v75 offset1:1
	s_waitcnt vmcnt(8)
	v_add_u32_e32 v49, 0x410, v15
	v_add_u32_e32 v0, 0x418, v15
	ds_write2_b32 v15, v76, v77 offset1:1
	ds_write2_b32 v15, v78, v79 offset0:2 offset1:3
	ds_write2_b32 v49, v80, v81 offset1:1
	ds_write2_b32 v0, v82, v83 offset1:1
	v_add_u32_e32 v49, 0x820, v15
	v_add_u32_e32 v0, 0x828, v15
	ds_write2_b32 v49, v84, v85 offset1:1
	ds_write2_b32 v0, v86, v87 offset1:1
	v_add_u32_e32 v49, 0xc30, v15
	v_add_u32_e32 v0, 0xc38, v15
	v_add_u32_e32 v15, 0x1040, v15
	ds_write2_b32 v49, v88, v89 offset1:1
	ds_write2_b32 v0, v90, v91 offset1:1
	s_waitcnt vmcnt(4)
	v_add_u32_e32 v49, 0x410, v15
	v_add_u32_e32 v0, 0x418, v15
	ds_write2_b32 v15, v92, v93 offset1:1
	ds_write2_b32 v15, v94, v95 offset0:2 offset1:3
	ds_write2_b32 v49, v96, v97 offset1:1
	ds_write2_b32 v0, v98, v99 offset1:1
	v_add_u32_e32 v49, 0x820, v15
	v_add_u32_e32 v0, 0x828, v15
	ds_write2_b32 v49, v100, v101 offset1:1
	ds_write2_b32 v0, v102, v103 offset1:1
	v_add_u32_e32 v49, 0xc30, v15
	v_add_u32_e32 v0, 0xc38, v15
	v_add_u32_e32 v15, 0x1040, v15
	ds_write2_b32 v49, v104, v105 offset1:1
	ds_write2_b32 v0, v106, v107 offset1:1
	s_waitcnt vmcnt(0)
	v_add_u32_e32 v49, 0x410, v15
	v_add_u32_e32 v0, 0x418, v15
	ds_write2_b32 v15, v108, v109 offset1:1
	ds_write2_b32 v15, v110, v111 offset0:2 offset1:3
	ds_write2_b32 v49, v112, v113 offset1:1
	ds_write2_b32 v0, v114, v115 offset1:1
	v_add_u32_e32 v49, 0x820, v15
	v_add_u32_e32 v0, 0x828, v15
	ds_write2_b32 v49, v116, v117 offset1:1
	ds_write2_b32 v0, v118, v119 offset1:1
	v_add_u32_e32 v49, 0xc30, v15
	v_add_u32_e32 v0, 0xc38, v15
	v_add_u32_e32 v15, 0x1040, v15
	ds_write2_b32 v49, v120, v121 offset1:1
	ds_write2_b32 v0, v122, v123 offset1:1
	s_add_u32 s18, s18, 0x100
	s_addc_u32 s19, s19, 0
	s_waitcnt lgkmcnt(0)

; #define LAS __attribute__((address_space(3)))
; __device__ __forceinline__ unsigned pk2(float lo, float hi) { return pg8::cvt_pk_bf16(lo, hi); }
; __device__ __forceinline__ void transpose_item(const float* W, int ldw, int K, const float* gain, bf16* WT, int kb, int scol0, int drow0, LAS float* scr, int lane) {
;     const int k0 = 64 * kb;
; #pragma unroll 4
;     for (int i = 0; i < 16; ++i) { const int kk = 4 * i + (lane >> 4); f32x4 w = *(const f32x4*)(W + (size_t)(k0 + kk) * ldw + scol0 + 4 * (lane & 15)); if (gain) w = w * gain[k0 + kk];
;         LAS float* d = scr + kk * 65 + 4 * (lane & 15); d[0] = w[0]; d[1] = w[1]; d[2] = w[2]; d[3] = w[3]; }
;     asm volatile("s_waitcnt lgkmcnt(0)" ::: "memory");
;     const int c = lane & 7;
; #pragma unroll
;     for (int j = 0; j < 8; ++j) { const int n = (lane >> 3) + 8 * j; const LAS float* p = scr + (8 * c) * 65 + n;
;         v4u o; o.x = pk2(p[0 * 65], p[1 * 65]); o.y = pk2(p[2 * 65], p[3 * 65]); o.z = pk2(p[4 * 65], p[5 * 65]); o.w = pk2(p[6 * 65], p[7 * 65]);
;         *(v4u*)(WT + (size_t)(drow0 + n) * K + k0 + 8 * c) = o; }
.LBB0_163:
	v_lshl_add_u64 v[20:21], v[18:19], 0, s[16:17]
	global_load_dwordx4 v[60:63], v[20:21], off
	v_lshl_add_u64 v[20:21], v[16:17], 0, s[16:17]
	global_load_dwordx4 v[64:67], v[20:21], off
	v_lshl_add_u64 v[20:21], v[2:3], 0, s[16:17]
	global_load_dwordx4 v[68:71], v[20:21], off
	v_lshl_add_u64 v[20:21], v[0:1], 0, s[16:17]
	global_load_dwordx4 v[72:75], v[20:21], off
	s_add_u32 s16, s16, 0x10000
	s_addc_u32 s17, s17, 0
	v_lshl_add_u64 v[20:21], v[18:19], 0, s[16:17]
	global_load_dwordx4 v[76:79], v[20:21], off
	v_lshl_add_u64 v[20:21], v[16:17], 0, s[16:17]
	global_load_dwordx4 v[80:83], v[20:21], off
	v_lshl_add_u64 v[20:21], v[2:3], 0, s[16:17]
	global_load_dwordx4 v[84:87], v[20:21], off
	v_lshl_add_u64 v[20:21], v[0:1], 0, s[16:17]
	global_load_dwordx4 v[88:91], v[20:21], off
	s_add_u32 s16, s16, 0x10000
	s_addc_u32 s17, s17, 0
	v_lshl_add_u64 v[20:21], v[18:19], 0, s[16:17]
	global_load_dwordx4 v[92:95], v[20:21], off
	v_lshl_add_u64 v[20:21], v[16:17], 0, s[16:17]
	global_load_dwordx4 v[96:99], v[20:21], off
	v_lshl_add_u64 v[20:21], v[2:3], 0, s[16:17]
	global_load_dwordx4 v[100:103], v[20:21], off
	v_lshl_add_u64 v[20:21], v[0:1], 0, s[16:17]
	global_load_dwordx4 v[104:107], v[20:21], off
	s_add_u32 s16, s16, 0x10000
	s_addc_u32 s17, s17, 0
	v_lshl_add_u64 v[20:21], v[18:19], 0, s[16:17]
	global_load_dwordx4 v[108:111], v[20:21], off
	v_lshl_add_u64 v[20:21], v[16:17], 0, s[16:17]
	global_load_dwordx4 v[112:115], v[20:21], off
	v_lshl_add_u64 v[20:21], v[2:3], 0, s[16:17]
	global_load_dwordx4 v[116:119], v[20:21], off
	v_lshl_add_u64 v[20:21], v[0:1], 0, s[16:17]
	global_load_dwordx4 v[120:123], v[20:21], off
	s_add_u32 s16, s16, 0x10000
	s_addc_u32 s17, s17, 0
	s_waitcnt vmcnt(12)
	v_add_u32_e32 v15, 0x410, v6
	v_add_u32_e32 v26, 0x418, v6
	ds_write2_b32 v6, v60, v61 offset1:1
	ds_write2_b32 v6, v62, v63 offset0:2 offset1:3
	ds_write2_b32 v15, v64, v65 offset1:1
	ds_write2_b32 v26, v66, v67 offset1:1
	v_add_u32_e32 v15, 0x820, v6
	v_add_u32_e32 v26, 0x828, v6
	ds_write2_b32 v15, v68, v69 offset1:1
	ds_write2_b32 v26, v70, v71 offset1:1
	v_add_u32_e32 v15, 0xc30, v6
	v_add_u32_e32 v24, 0xc38, v6
	v_add_u32_e32 v6, 0x1040, v6
	ds_write2_b32 v15, v72, v73 offset1:1
	ds_write2_b32 v24, v74, v75 offset1:1
	s_waitcnt vmcnt(8)
	v_add_u32_e32 v15, 0x410, v6
	v_add_u32_e32 v26, 0x418, v6
	ds_write2_b32 v6, v76, v77 offset1:1
	ds_write2_b32 v6, v78, v79 offset0:2 offset1:3
	ds_write2_b32 v15, v80, v81 offset1:1
	ds_write2_b32 v26, v82, v83 offset1:1
	v_add_u32_e32 v15, 0x820, v6
	v_add_u32_e32 v26, 0x828, v6
	ds_write2_b32 v15, v84, v85 offset1:1
	ds_write2_b32 v26, v86, v87 offset1:1
	v_add_u32_e32 v15, 0xc30, v6
	v_add_u32_e32 v24, 0xc38, v6
	v_add_u32_e32 v6, 0x1040, v6
	ds_write2_b32 v15, v88, v89 offset1:1
	ds_write2_b32 v24, v90, v91 offset1:1
	s_waitcnt vmcnt(4)
	v_add_u32_e32 v15, 0x410, v6
	v_add_u32_e32 v26, 0x418, v6
	ds_write2_b32 v6, v92, v93 offset1:1
	ds_write2_b32 v6, v94, v95 offset0:2 offset1:3
	ds_write2_b32 v15, v96, v97 offset1:1
	ds_write2_b32 v26, v98, v99 offset1:1
	v_add_u32_e32 v15, 0x820, v6
	v_add_u32_e32 v26, 0x828, v6
	ds_write2_b32 v15, v100, v101 offset1:1
	ds_write2_b32 v26, v102, v103 offset1:1
	v_add_u32_e32 v15, 0xc30, v6
	v_add_u32_e32 v24, 0xc38, v6
	v_add_u32_e32 v6, 0x1040, v6
	ds_write2_b32 v15, v104, v105 offset1:1
	ds_write2_b32 v24, v106, v107 offset1:1
	s_waitcnt vmcnt(0)
	v_add_u32_e32 v15, 0x410, v6
	v_add_u32_e32 v26, 0x418, v6
	ds_write2_b32 v6, v108, v109 offset1:1
	ds_write2_b32 v6, v110, v111 offset0:2 offset1:3
	ds_write2_b32 v15, v112, v113 offset1:1
	ds_write2_b32 v26, v114, v115 offset1:1
	v_add_u32_e32 v15, 0x820, v6
	v_add_u32_e32 v26, 0x828, v6
	ds_write2_b32 v15, v116, v117 offset1:1
	ds_write2_b32 v26, v118, v119 offset1:1
	v_add_u32_e32 v15, 0xc30, v6
	v_add_u32_e32 v24, 0xc38, v6
	v_add_u32_e32 v6, 0x1040, v6
	ds_write2_b32 v15, v120, v121 offset1:1
	ds_write2_b32 v24, v122, v123 offset1:1
	s_waitcnt lgkmcnt(0)
	s_lshl_b32 s2, s31, 6
	s_lshl_b32 s17, s31, 2
	s_and_b32 s16, s2, 0x3c0
	s_and_b32 s2, s17, 0x1fc0
	s_addk_i32 s2, 0xec00
	s_waitcnt lgkmcnt(0)
	s_lshl_b64 s[18:19], s[2:3], 1
	ds_read2_b32 v[0:1], v29 offset1:65
	s_add_u32 s4, s4, s18
	s_waitcnt lgkmcnt(0)
	v_cvt_pk_bf16_f32 v0, v0, v1
	ds_read2_b32 v[2:3], v29 offset0:130 offset1:195
	v_lshlrev_b32_e32 v6, 1, v8
	v_add_u32_e32 v15, 0x400, v29
	s_addc_u32 s5, s5, s19
	s_waitcnt lgkmcnt(0)
; #define LAS __attribute__((address_space(3)))
; __device__ __forceinline__ unsigned pk2(float lo, float hi) { return pg8::cvt_pk_bf16(lo, hi); }
; __device__ __forceinline__ void transpose_item(const float* W, int ldw, int K, const float* gain, bf16* WT, int kb, int scol0, int drow0, LAS float* scr, int lane) {
;     ...
;     const int c = lane & 7;
; #pragma unroll
;     for (int j = 0; j < 8; ++j) { const int n = (lane >> 3) + 8 * j; const LAS float* p = scr + (8 * c) * 65 + n;
;         v4u o; o.x = pk2(p[0 * 65], p[1 * 65]); o.y = pk2(p[2 * 65], p[3 * 65]); o.z = pk2(p[4 * 65], p[5 * 65]); o.w = pk2(p[6 * 65], p[7 * 65]);
;         *(v4u*)(WT + (size_t)(drow0 + n) * K + k0 + 8 * c) = o; }
;     asm volatile("s_waitcnt lgkmcnt(0)" ::: "memory");
	v_cvt_pk_bf16_f32 v1, v2, v3
	ds_read2_b32 v[2:3], v15 offset0:4 offset1:69
	v_or_b32_e32 v20, s16, v28
	v_lshl_add_u64 v[18:19], s[4:5], 0, v[6:7]
	s_waitcnt lgkmcnt(0)
	v_cvt_pk_bf16_f32 v2, v2, v3
	ds_read2_b32 v[16:17], v15 offset0:134 offset1:199
	v_lshl_add_u64 v[18:19], v[18:19], 0, s[10:11]
	v_lshlrev_b32_e32 v6, 12, v20
	s_waitcnt lgkmcnt(0)
	v_cvt_pk_bf16_f32 v3, v16, v17
	v_lshl_add_u64 v[16:17], v[18:19], 0, v[6:7]
	flat_store_dwordx4 v[16:17], v[0:3]
	ds_read2_b32 v[0:1], v29 offset0:8 offset1:73
	s_waitcnt lgkmcnt(0)
	v_cvt_pk_bf16_f32 v0, v0, v1
	ds_read2_b32 v[2:3], v29 offset0:138 offset1:203
	s_waitcnt lgkmcnt(0)
	v_cvt_pk_bf16_f32 v1, v2, v3
	ds_read2_b32 v[2:3], v15 offset0:12 offset1:77
	s_waitcnt lgkmcnt(0)
	v_cvt_pk_bf16_f32 v2, v2, v3
	v_or_b32_e32 v3, s16, v30
	v_lshlrev_b32_e32 v6, 12, v3
	v_lshl_add_u64 v[20:21], v[18:19], 0, v[6:7]
	ds_read2_b32 v[16:17], v15 offset0:142 offset1:207
	s_waitcnt lgkmcnt(0)
	v_cvt_pk_bf16_f32 v3, v16, v17
	flat_store_dwordx4 v[20:21], v[0:3]
	ds_read2_b32 v[0:1], v29 offset0:16 offset1:81
	s_waitcnt lgkmcnt(0)
	v_cvt_pk_bf16_f32 v0, v0, v1
	ds_read2_b32 v[2:3], v29 offset0:146 offset1:211
	s_waitcnt lgkmcnt(0)
	v_cvt_pk_bf16_f32 v1, v2, v3
	ds_read2_b32 v[2:3], v15 offset0:20 offset1:85
	s_waitcnt lgkmcnt(0)
	v_cvt_pk_bf16_f32 v2, v2, v3
	v_or_b32_e32 v3, s16, v31
	v_lshlrev_b32_e32 v6, 12, v3
	v_lshl_add_u64 v[20:21], v[18:19], 0, v[6:7]
	ds_read2_b32 v[16:17], v15 offset0:150 offset1:215
	s_waitcnt lgkmcnt(0)
	v_cvt_pk_bf16_f32 v3, v16, v17
	flat_store_dwordx4 v[20:21], v[0:3]
	ds_read2_b32 v[0:1], v29 offset0:24 offset1:89
	s_waitcnt lgkmcnt(0)
	v_cvt_pk_bf16_f32 v0, v0, v1
	ds_read2_b32 v[2:3], v29 offset0:154 offset1:219
	s_waitcnt lgkmcnt(0)
	v_cvt_pk_bf16_f32 v1, v2, v3
	ds_read2_b32 v[2:3], v15 offset0:28 offset1:93
	s_waitcnt lgkmcnt(0)
	v_cvt_pk_bf16_f32 v2, v2, v3
	v_or_b32_e32 v3, s16, v32
	v_lshlrev_b32_e32 v6, 12, v3
	v_lshl_add_u64 v[20:21], v[18:19], 0, v[6:7]
	ds_read2_b32 v[16:17], v15 offset0:158 offset1:223
	s_waitcnt lgkmcnt(0)
	v_cvt_pk_bf16_f32 v3, v16, v17
	flat_store_dwordx4 v[20:21], v[0:3]
	ds_read2_b32 v[0:1], v29 offset0:32 offset1:97
	s_waitcnt lgkmcnt(0)
	v_cvt_pk_bf16_f32 v0, v0, v1
	ds_read2_b32 v[2:3], v29 offset0:162 offset1:227
	s_waitcnt lgkmcnt(0)
	v_cvt_pk_bf16_f32 v1, v2, v3
	ds_read2_b32 v[2:3], v15 offset0:36 offset1:101
	s_waitcnt lgkmcnt(0)
	v_cvt_pk_bf16_f32 v2, v2, v3
	v_or_b32_e32 v3, s16, v33
	v_lshlrev_b32_e32 v6, 12, v3
	v_lshl_add_u64 v[20:21], v[18:19], 0, v[6:7]
	ds_read2_b32 v[16:17], v15 offset0:166 offset1:231
	s_waitcnt lgkmcnt(0)
	v_cvt_pk_bf16_f32 v3, v16, v17
	flat_store_dwordx4 v[20:21], v[0:3]
	ds_read2_b32 v[0:1], v29 offset0:40 offset1:105
	s_waitcnt lgkmcnt(0)
	v_cvt_pk_bf16_f32 v0, v0, v1
	ds_read2_b32 v[2:3], v29 offset0:170 offset1:235
	s_waitcnt lgkmcnt(0)
	v_cvt_pk_bf16_f32 v1, v2, v3
	ds_read2_b32 v[2:3], v15 offset0:44 offset1:109
	s_waitcnt lgkmcnt(0)
	v_cvt_pk_bf16_f32 v2, v2, v3
	v_or_b32_e32 v3, s16, v34
	v_lshlrev_b32_e32 v6, 12, v3
	v_lshl_add_u64 v[20:21], v[18:19], 0, v[6:7]
	ds_read2_b32 v[16:17], v15 offset0:174 offset1:239
	s_waitcnt lgkmcnt(0)
	v_cvt_pk_bf16_f32 v3, v16, v17
	flat_store_dwordx4 v[20:21], v[0:3]
	ds_read2_b32 v[0:1], v29 offset0:48 offset1:113
	s_waitcnt lgkmcnt(0)
	v_cvt_pk_bf16_f32 v0, v0, v1
	ds_read2_b32 v[2:3], v29 offset0:178 offset1:243
	s_waitcnt lgkmcnt(0)
	v_cvt_pk_bf16_f32 v1, v2, v3
	ds_read2_b32 v[2:3], v15 offset0:52 offset1:117
	s_waitcnt lgkmcnt(0)
	v_cvt_pk_bf16_f32 v2, v2, v3
	v_or_b32_e32 v3, s16, v35
	v_lshlrev_b32_e32 v6, 12, v3
	v_lshl_add_u64 v[20:21], v[18:19], 0, v[6:7]
	ds_read2_b32 v[16:17], v15 offset0:182 offset1:247
	s_waitcnt lgkmcnt(0)
	v_cvt_pk_bf16_f32 v3, v16, v17
	flat_store_dwordx4 v[20:21], v[0:3]
	ds_read2_b32 v[0:1], v29 offset0:56 offset1:121
	s_waitcnt lgkmcnt(0)
	v_cvt_pk_bf16_f32 v0, v0, v1
	ds_read2_b32 v[2:3], v29 offset0:186 offset1:251
	s_waitcnt lgkmcnt(0)
	v_cvt_pk_bf16_f32 v1, v2, v3
	ds_read2_b32 v[2:3], v15 offset0:60 offset1:125
	s_waitcnt lgkmcnt(0)
	v_cvt_pk_bf16_f32 v2, v2, v3
	v_or_b32_e32 v3, s16, v36
	ds_read2_b32 v[16:17], v15 offset0:190 offset1:255
	v_lshlrev_b32_e32 v6, 12, v3
	s_waitcnt lgkmcnt(0)
	v_cvt_pk_bf16_f32 v3, v16, v17
	v_lshl_add_u64 v[16:17], v[18:19], 0, v[6:7]
	flat_store_dwordx4 v[16:17], v[0:3]
	s_waitcnt lgkmcnt(0)

; #define LAS __attribute__((address_space(3)))
; __device__ __forceinline__ void transpose_item(const float* W, int ldw, int K, const float* gain, bf16* WT, int kb, int scol0, int drow0, LAS float* scr, int lane) {
;     const int k0 = 64 * kb;
; #pragma unroll 4
;     for (int i = 0; i < 16; ++i) { const int kk = 4 * i + (lane >> 4); f32x4 w = *(const f32x4*)(W + (size_t)(k0 + kk) * ldw + scol0 + 4 * (lane & 15)); if (gain) w = w * gain[k0 + kk];
;         LAS float* d = scr + kk * 65 + 4 * (lane & 15); d[0] = w[0]; d[1] = w[1]; d[2] = w[2]; d[3] = w[3]; }
;     asm volatile("s_waitcnt lgkmcnt(0)" ::: "memory");
.LBB0_171:
	v_mov_b32_e32 v20, v2
	v_ashrrev_i32_e32 v21, 31, v20
	v_lshlrev_b64 v[20:21], 12, v[20:21]
	v_lshl_add_u64 v[20:21], v[0:1], 0, v[20:21]
	global_load_dwordx4 v[60:63], v[20:21], off
	v_add_u32_e32 v20, 4, v2
	v_ashrrev_i32_e32 v21, 31, v20
	v_lshlrev_b64 v[20:21], 12, v[20:21]
	v_lshl_add_u64 v[20:21], v[0:1], 0, v[20:21]
	global_load_dwordx4 v[64:67], v[20:21], off
	v_add_u32_e32 v20, 8, v2
	v_ashrrev_i32_e32 v21, 31, v20
	v_lshlrev_b64 v[20:21], 12, v[20:21]
	v_lshl_add_u64 v[20:21], v[0:1], 0, v[20:21]
	global_load_dwordx4 v[68:71], v[20:21], off
	v_add_u32_e32 v20, 12, v2
	v_ashrrev_i32_e32 v21, 31, v20
	v_lshlrev_b64 v[20:21], 12, v[20:21]
	v_lshl_add_u64 v[20:21], v[0:1], 0, v[20:21]
	global_load_dwordx4 v[72:75], v[20:21], off
	v_add_u32_e32 v20, 16, v2
	v_ashrrev_i32_e32 v21, 31, v20
	v_lshlrev_b64 v[20:21], 12, v[20:21]
	v_lshl_add_u64 v[20:21], v[0:1], 0, v[20:21]
	global_load_dwordx4 v[76:79], v[20:21], off
	v_add_u32_e32 v20, 20, v2
	v_ashrrev_i32_e32 v21, 31, v20
	v_lshlrev_b64 v[20:21], 12, v[20:21]
	v_lshl_add_u64 v[20:21], v[0:1], 0, v[20:21]
	global_load_dwordx4 v[80:83], v[20:21], off
	v_add_u32_e32 v20, 24, v2
	v_ashrrev_i32_e32 v21, 31, v20
	v_lshlrev_b64 v[20:21], 12, v[20:21]
	v_lshl_add_u64 v[20:21], v[0:1], 0, v[20:21]
	global_load_dwordx4 v[84:87], v[20:21], off
	v_add_u32_e32 v20, 28, v2
	v_ashrrev_i32_e32 v21, 31, v20
	v_lshlrev_b64 v[20:21], 12, v[20:21]
	v_lshl_add_u64 v[20:21], v[0:1], 0, v[20:21]
	global_load_dwordx4 v[88:91], v[20:21], off
	v_add_u32_e32 v20, 32, v2
	v_ashrrev_i32_e32 v21, 31, v20
	v_lshlrev_b64 v[20:21], 12, v[20:21]
	v_lshl_add_u64 v[20:21], v[0:1], 0, v[20:21]
	global_load_dwordx4 v[92:95], v[20:21], off
	v_add_u32_e32 v20, 36, v2
	v_ashrrev_i32_e32 v21, 31, v20
	v_lshlrev_b64 v[20:21], 12, v[20:21]
	v_lshl_add_u64 v[20:21], v[0:1], 0, v[20:21]
	global_load_dwordx4 v[96:99], v[20:21], off
	v_add_u32_e32 v20, 40, v2
	v_ashrrev_i32_e32 v21, 31, v20
	v_lshlrev_b64 v[20:21], 12, v[20:21]
	v_lshl_add_u64 v[20:21], v[0:1], 0, v[20:21]
	global_load_dwordx4 v[100:103], v[20:21], off
	v_add_u32_e32 v20, 44, v2
	v_ashrrev_i32_e32 v21, 31, v20
	v_lshlrev_b64 v[20:21], 12, v[20:21]
	v_lshl_add_u64 v[20:21], v[0:1], 0, v[20:21]
	global_load_dwordx4 v[104:107], v[20:21], off
	v_add_u32_e32 v20, 48, v2
	v_ashrrev_i32_e32 v21, 31, v20
	v_lshlrev_b64 v[20:21], 12, v[20:21]
	v_lshl_add_u64 v[20:21], v[0:1], 0, v[20:21]
	global_load_dwordx4 v[108:111], v[20:21], off
	v_add_u32_e32 v20, 52, v2
	v_ashrrev_i32_e32 v21, 31, v20
	v_lshlrev_b64 v[20:21], 12, v[20:21]
	v_lshl_add_u64 v[20:21], v[0:1], 0, v[20:21]
	global_load_dwordx4 v[112:115], v[20:21], off
	v_add_u32_e32 v20, 56, v2
	v_ashrrev_i32_e32 v21, 31, v20
	v_lshlrev_b64 v[20:21], 12, v[20:21]
	v_lshl_add_u64 v[20:21], v[0:1], 0, v[20:21]
	global_load_dwordx4 v[116:119], v[20:21], off
	v_add_u32_e32 v20, 60, v2
	v_ashrrev_i32_e32 v21, 31, v20
	v_lshlrev_b64 v[20:21], 12, v[20:21]
	v_lshl_add_u64 v[20:21], v[0:1], 0, v[20:21]
	global_load_dwordx4 v[120:123], v[20:21], off
	s_mov_b32 s2, 64
	s_waitcnt vmcnt(12)
	v_add_u32_e32 v6, 0x410, v3
	v_add_u32_e32 v15, 0x418, v3
	ds_write2_b32 v3, v60, v61 offset1:1
	ds_write2_b32 v3, v62, v63 offset0:2 offset1:3
	ds_write2_b32 v6, v64, v65 offset1:1
	ds_write2_b32 v15, v66, v67 offset1:1
	v_add_u32_e32 v6, 0x820, v3
	v_add_u32_e32 v15, 0x828, v3
	ds_write2_b32 v6, v68, v69 offset1:1
	ds_write2_b32 v15, v70, v71 offset1:1
	v_add_u32_e32 v6, 0xc30, v3
	v_add_u32_e32 v15, 0xc38, v3
	v_add_u32_e32 v3, 0x1040, v3
	ds_write2_b32 v6, v72, v73 offset1:1
	ds_write2_b32 v15, v74, v75 offset1:1
	s_waitcnt vmcnt(8)
	v_add_u32_e32 v6, 0x410, v3
	v_add_u32_e32 v15, 0x418, v3
	ds_write2_b32 v3, v76, v77 offset1:1
	ds_write2_b32 v3, v78, v79 offset0:2 offset1:3
	ds_write2_b32 v6, v80, v81 offset1:1
	ds_write2_b32 v15, v82, v83 offset1:1
	v_add_u32_e32 v6, 0x820, v3
	v_add_u32_e32 v15, 0x828, v3
	ds_write2_b32 v6, v84, v85 offset1:1
	ds_write2_b32 v15, v86, v87 offset1:1
	v_add_u32_e32 v6, 0xc30, v3
	v_add_u32_e32 v15, 0xc38, v3
	v_add_u32_e32 v3, 0x1040, v3
	ds_write2_b32 v6, v88, v89 offset1:1
	ds_write2_b32 v15, v90, v91 offset1:1
	s_waitcnt vmcnt(4)
	v_add_u32_e32 v6, 0x410, v3
	v_add_u32_e32 v15, 0x418, v3
	ds_write2_b32 v3, v92, v93 offset1:1
	ds_write2_b32 v3, v94, v95 offset0:2 offset1:3
	ds_write2_b32 v6, v96, v97 offset1:1
	ds_write2_b32 v15, v98, v99 offset1:1
	v_add_u32_e32 v6, 0x820, v3
	v_add_u32_e32 v15, 0x828, v3
	ds_write2_b32 v6, v100, v101 offset1:1
	ds_write2_b32 v15, v102, v103 offset1:1
	v_add_u32_e32 v6, 0xc30, v3
	v_add_u32_e32 v15, 0xc38, v3
	v_add_u32_e32 v3, 0x1040, v3
	ds_write2_b32 v6, v104, v105 offset1:1
	ds_write2_b32 v15, v106, v107 offset1:1
	s_waitcnt vmcnt(0)
	v_add_u32_e32 v6, 0x410, v3
	v_add_u32_e32 v15, 0x418, v3
	ds_write2_b32 v3, v108, v109 offset1:1
	ds_write2_b32 v3, v110, v111 offset0:2 offset1:3
	ds_write2_b32 v6, v112, v113 offset1:1
	ds_write2_b32 v15, v114, v115 offset1:1
	v_add_u32_e32 v6, 0x820, v3
	v_add_u32_e32 v15, 0x828, v3
	ds_write2_b32 v6, v116, v117 offset1:1
	ds_write2_b32 v15, v118, v119 offset1:1
	v_add_u32_e32 v6, 0xc30, v3
	v_add_u32_e32 v15, 0xc38, v3
	v_add_u32_e32 v3, 0x1040, v3
	ds_write2_b32 v6, v120, v121 offset1:1
	ds_write2_b32 v15, v122, v123 offset1:1
	s_waitcnt lgkmcnt(0)
; #define LAS __attribute__((address_space(3)))
; __device__ __forceinline__ unsigned pk2(float lo, float hi) { return pg8::cvt_pk_bf16(lo, hi); }
; __device__ __forceinline__ void transpose_item(const float* W, int ldw, int K, const float* gain, bf16* WT, int kb, int scol0, int drow0, LAS float* scr, int lane) {
;     ...
;     const int c = lane & 7;
; #pragma unroll
;     for (int j = 0; j < 8; ++j) { const int n = (lane >> 3) + 8 * j; const LAS float* p = scr + (8 * c) * 65 + n;
;         v4u o; o.x = pk2(p[0 * 65], p[1 * 65]); o.y = pk2(p[2 * 65], p[3 * 65]); o.z = pk2(p[4 * 65], p[5 * 65]); o.w = pk2(p[6 * 65], p[7 * 65]);
;         *(v4u*)(WT + (size_t)(drow0 + n) * K + k0 + 8 * c) = o; }
;     asm volatile("s_waitcnt lgkmcnt(0)" ::: "memory");
; }
	s_ashr_i32 s19, s18, 31
	s_lshl_b64 s[18:19], s[18:19], 1
	s_waitcnt lgkmcnt(0)
	s_add_u32 s16, s16, s18
	ds_read2_b32 v[0:1], v29 offset1:65
	v_lshlrev_b32_e32 v6, 1, v8
	v_or_b32_e32 v16, s4, v28
	s_addc_u32 s17, s17, s19
	s_waitcnt lgkmcnt(0)
	v_cvt_pk_bf16_f32 v0, v0, v1
	ds_read2_b32 v[2:3], v29 offset0:130 offset1:195
	v_add_u32_e32 v15, 0x400, v29
	v_ashrrev_i32_e32 v17, 31, v16
	v_lshl_add_u64 v[20:21], s[16:17], 0, v[6:7]
	s_waitcnt lgkmcnt(0)
	v_cvt_pk_bf16_f32 v1, v2, v3
	ds_read2_b32 v[2:3], v15 offset0:4 offset1:69
	v_lshlrev_b64 v[16:17], 11, v[16:17]
	v_lshl_add_u64 v[20:21], v[20:21], 0, s[14:15]
	s_waitcnt lgkmcnt(0)
	v_cvt_pk_bf16_f32 v2, v2, v3
	ds_read2_b32 v[18:19], v15 offset0:134 offset1:199
	v_lshl_add_u64 v[16:17], v[20:21], 0, v[16:17]
	s_waitcnt lgkmcnt(0)
	v_cvt_pk_bf16_f32 v3, v18, v19
	flat_store_dwordx4 v[16:17], v[0:3]
	v_or_b32_e32 v18, s4, v30
	ds_read2_b32 v[0:1], v29 offset0:8 offset1:73
	v_ashrrev_i32_e32 v19, 31, v18
	s_waitcnt lgkmcnt(0)
	v_cvt_pk_bf16_f32 v0, v0, v1
	ds_read2_b32 v[2:3], v29 offset0:138 offset1:203
	v_lshlrev_b64 v[18:19], 11, v[18:19]
	s_waitcnt lgkmcnt(0)
	v_cvt_pk_bf16_f32 v1, v2, v3
	ds_read2_b32 v[2:3], v15 offset0:12 offset1:77
	v_lshl_add_u64 v[18:19], v[20:21], 0, v[18:19]
	s_waitcnt lgkmcnt(0)
	v_cvt_pk_bf16_f32 v2, v2, v3
	ds_read2_b32 v[16:17], v15 offset0:142 offset1:207
	s_waitcnt lgkmcnt(0)
	v_cvt_pk_bf16_f32 v3, v16, v17
	flat_store_dwordx4 v[18:19], v[0:3]
	v_or_b32_e32 v18, s4, v31
	ds_read2_b32 v[0:1], v29 offset0:16 offset1:81
	v_ashrrev_i32_e32 v19, 31, v18
	s_waitcnt lgkmcnt(0)
	v_cvt_pk_bf16_f32 v0, v0, v1
	ds_read2_b32 v[2:3], v29 offset0:146 offset1:211
	v_lshlrev_b64 v[18:19], 11, v[18:19]
	s_waitcnt lgkmcnt(0)
	v_cvt_pk_bf16_f32 v1, v2, v3
	ds_read2_b32 v[2:3], v15 offset0:20 offset1:85
	v_lshl_add_u64 v[18:19], v[20:21], 0, v[18:19]
	s_waitcnt lgkmcnt(0)
	v_cvt_pk_bf16_f32 v2, v2, v3
	ds_read2_b32 v[16:17], v15 offset0:150 offset1:215
	s_waitcnt lgkmcnt(0)
	v_cvt_pk_bf16_f32 v3, v16, v17
	flat_store_dwordx4 v[18:19], v[0:3]
	v_or_b32_e32 v18, s4, v32
	ds_read2_b32 v[0:1], v29 offset0:24 offset1:89
	v_ashrrev_i32_e32 v19, 31, v18
	s_waitcnt lgkmcnt(0)
	v_cvt_pk_bf16_f32 v0, v0, v1
	ds_read2_b32 v[2:3], v29 offset0:154 offset1:219
	v_lshlrev_b64 v[18:19], 11, v[18:19]
	s_waitcnt lgkmcnt(0)
	v_cvt_pk_bf16_f32 v1, v2, v3
	ds_read2_b32 v[2:3], v15 offset0:28 offset1:93
	v_lshl_add_u64 v[18:19], v[20:21], 0, v[18:19]
	s_waitcnt lgkmcnt(0)
	v_cvt_pk_bf16_f32 v2, v2, v3
	ds_read2_b32 v[16:17], v15 offset0:158 offset1:223
	s_waitcnt lgkmcnt(0)
	v_cvt_pk_bf16_f32 v3, v16, v17
	flat_store_dwordx4 v[18:19], v[0:3]
	v_or_b32_e32 v18, s4, v33
	ds_read2_b32 v[0:1], v29 offset0:32 offset1:97
	v_ashrrev_i32_e32 v19, 31, v18
	s_waitcnt lgkmcnt(0)
	v_cvt_pk_bf16_f32 v0, v0, v1
	ds_read2_b32 v[2:3], v29 offset0:162 offset1:227
	v_lshlrev_b64 v[18:19], 11, v[18:19]
	s_waitcnt lgkmcnt(0)
	v_cvt_pk_bf16_f32 v1, v2, v3
	ds_read2_b32 v[2:3], v15 offset0:36 offset1:101
	v_lshl_add_u64 v[18:19], v[20:21], 0, v[18:19]
	s_waitcnt lgkmcnt(0)
	v_cvt_pk_bf16_f32 v2, v2, v3
	ds_read2_b32 v[16:17], v15 offset0:166 offset1:231
	s_waitcnt lgkmcnt(0)
	v_cvt_pk_bf16_f32 v3, v16, v17
	flat_store_dwordx4 v[18:19], v[0:3]
	v_or_b32_e32 v18, s4, v34
	ds_read2_b32 v[0:1], v29 offset0:40 offset1:105
	v_ashrrev_i32_e32 v19, 31, v18
	s_waitcnt lgkmcnt(0)
	v_cvt_pk_bf16_f32 v0, v0, v1
	ds_read2_b32 v[2:3], v29 offset0:170 offset1:235
	v_lshlrev_b64 v[18:19], 11, v[18:19]
	s_waitcnt lgkmcnt(0)
	v_cvt_pk_bf16_f32 v1, v2, v3
	ds_read2_b32 v[2:3], v15 offset0:44 offset1:109
	v_lshl_add_u64 v[18:19], v[20:21], 0, v[18:19]
	s_waitcnt lgkmcnt(0)
	v_cvt_pk_bf16_f32 v2, v2, v3
	ds_read2_b32 v[16:17], v15 offset0:174 offset1:239
	s_waitcnt lgkmcnt(0)
	v_cvt_pk_bf16_f32 v3, v16, v17
	flat_store_dwordx4 v[18:19], v[0:3]
	v_or_b32_e32 v18, s4, v35
	ds_read2_b32 v[0:1], v29 offset0:48 offset1:113
	v_ashrrev_i32_e32 v19, 31, v18
	s_waitcnt lgkmcnt(0)
	v_cvt_pk_bf16_f32 v0, v0, v1
	ds_read2_b32 v[2:3], v29 offset0:178 offset1:243
	v_lshlrev_b64 v[18:19], 11, v[18:19]
	s_waitcnt lgkmcnt(0)
	v_cvt_pk_bf16_f32 v1, v2, v3
	ds_read2_b32 v[2:3], v15 offset0:52 offset1:117
	v_lshl_add_u64 v[18:19], v[20:21], 0, v[18:19]
	s_waitcnt lgkmcnt(0)
	v_cvt_pk_bf16_f32 v2, v2, v3
	ds_read2_b32 v[16:17], v15 offset0:182 offset1:247
	s_waitcnt lgkmcnt(0)
	v_cvt_pk_bf16_f32 v3, v16, v17
	flat_store_dwordx4 v[18:19], v[0:3]
	ds_read2_b32 v[0:1], v29 offset0:56 offset1:121
	v_or_b32_e32 v18, s4, v36
	s_waitcnt lgkmcnt(0)
	v_cvt_pk_bf16_f32 v0, v0, v1
	ds_read2_b32 v[2:3], v29 offset0:186 offset1:251
	s_waitcnt lgkmcnt(0)
	v_cvt_pk_bf16_f32 v1, v2, v3
	ds_read2_b32 v[2:3], v15 offset0:60 offset1:125
	v_ashrrev_i32_e32 v19, 31, v18
	s_waitcnt lgkmcnt(0)
	v_cvt_pk_bf16_f32 v2, v2, v3
	ds_read2_b32 v[16:17], v15 offset0:190 offset1:255
	v_lshlrev_b64 v[18:19], 11, v[18:19]
	s_waitcnt lgkmcnt(0)
	v_cvt_pk_bf16_f32 v3, v16, v17
	v_lshl_add_u64 v[16:17], v[20:21], 0, v[18:19]
	flat_store_dwordx4 v[16:17], v[0:3]
	s_waitcnt lgkmcnt(0)
	s_branch .LBB0_140
